# peel first K iteration of all 4 GEMM loops with SrcC=0 on first-touch MFMAs; accumulator zeroing removed
# speedup vs baseline: 1.0074x; 1.0002x over previous
.LBB0_124:
	s_ashr_i32 s79, s78, 31
	s_lshl_b64 s[10:11], s[78:79], 19
	s_add_u32 s80, s54, s10
	v_cmp_lt_i64_e32 vcc, s[72:73], v[178:179]
	s_addc_u32 s81, s55, s11
	s_and_b64 s[10:11], vcc, exec
	s_cselect_b32 s1, s81, s87
	s_cselect_b32 s10, s80, s86
	s_ashr_i32 s77, s76, 31
	s_lshl_b64 s[36:37], s[76:77], 19
	s_add_u32 s72, s66, s36
	s_addc_u32 s73, s59, s37
	s_and_b64 s[36:37], vcc, exec
	s_cselect_b32 s11, s73, s83
	s_cselect_b32 s25, s72, s82
	s_add_u32 s86, s86, 0x40080
	s_addc_u32 s87, s87, 0
	s_add_u32 s33, s82, 0x100
	s_addc_u32 s36, s83, 0
	s_mov_b32 s37, -2
	s_add_u32 s27, s86, 0xfffc0080
	s_addc_u32 s56, s87, -1
	s_add_i32 s57, 0, 0x10000
	v_add_u32_e32 v76, s57, v217
	ds_read_b128 v[64:67], v76
	ds_read_b128 v[68:71], v76 offset:1024
	ds_read_b128 v[72:75], v76 offset:2048
	ds_read_b128 v[76:79], v76 offset:3072
	s_cmp_eq_u32 s37, 12
	s_cselect_b32 vcc_hi, s1, s56
	s_cselect_b32 vcc_lo, s10, s27
	s_cselect_b32 s83, s11, s36
	s_cselect_b32 s82, s25, s33
	v_lshl_add_u64 v[168:169], s[86:87], 0, v[164:165]
	s_add_i32 m0, s75, 0xc000
	ds_read_b128 v[80:83], v220
	ds_read_b128 v[84:87], v220 offset:1024
	ds_read_b128 v[88:91], v220 offset:2048
	ds_read_b128 v[92:95], v220 offset:3072
	ds_read_b128 v[188:191], v220 offset:4096
	ds_read_b128 v[192:195], v220 offset:5120
	ds_read_b128 v[196:199], v220 offset:6144
	ds_read_b128 v[200:203], v220 offset:7168
	global_load_lds_dwordx4 v[168:169], off
	v_lshl_add_u64 v[168:169], s[86:87], 0, v[166:167]
	s_add_i32 m0, s75, 0xe000
	s_nop 0
	global_load_lds_dwordx4 v[168:169], off
	s_waitcnt lgkmcnt(8)
	s_barrier
	s_waitcnt lgkmcnt(0)
	s_setprio 1
	s_waitcnt lgkmcnt(0)
	v_mfma_f32_16x16x32_bf16 v[146:149], v[64:67], v[80:83], 0
	v_mfma_f32_16x16x32_bf16 v[116:119], v[72:75], v[80:83], 0
	v_mfma_f32_16x16x32_bf16 v[158:161], v[64:67], v[88:91], 0
	v_mfma_f32_16x16x32_bf16 v[124:127], v[72:75], v[88:91], 0
	v_mfma_f32_16x16x32_bf16 v[154:157], v[64:67], v[188:191], 0
	v_mfma_f32_16x16x32_bf16 v[112:115], v[72:75], v[188:191], 0
	v_mfma_f32_16x16x32_bf16 v[150:153], v[64:67], v[196:199], 0
	v_mfma_f32_16x16x32_bf16 v[120:123], v[72:75], v[196:199], 0
	v_mfma_f32_16x16x32_bf16 v[146:149], v[68:71], v[84:87], v[146:149]
	v_mfma_f32_16x16x32_bf16 v[116:119], v[76:79], v[84:87], v[116:119]
	v_mfma_f32_16x16x32_bf16 v[158:161], v[68:71], v[92:95], v[158:161]
	v_mfma_f32_16x16x32_bf16 v[124:127], v[76:79], v[92:95], v[124:127]
	v_mfma_f32_16x16x32_bf16 v[154:157], v[68:71], v[192:195], v[154:157]
	v_mfma_f32_16x16x32_bf16 v[112:115], v[76:79], v[192:195], v[112:115]
	v_mfma_f32_16x16x32_bf16 v[150:153], v[68:71], v[200:203], v[150:153]
	v_mfma_f32_16x16x32_bf16 v[120:123], v[76:79], v[200:203], v[120:123]
	s_setprio 0
	s_barrier
	s_add_i32 s27, 0, 0x14000
	v_add_u32_e32 v168, s27, v217
	s_add_i32 s56, s57, s74
	ds_read_b128 v[204:207], v168
	ds_read_b128 v[222:225], v168 offset:1024
	ds_read_b128 v[228:231], v168 offset:2048
	ds_read_b128 v[232:235], v168 offset:3072
	v_lshl_add_u64 v[168:169], s[82:83], 0, v[144:145]
	s_mov_b32 m0, s56
	v_lshl_add_u64 v[176:177], s[82:83], 0, v[162:163]
	global_load_lds_dwordx4 v[168:169], off
	s_add_i32 m0, s56, 0x2000
	s_nop 0
	global_load_lds_dwordx4 v[176:177], off
	s_barrier
	s_waitcnt lgkmcnt(0)
	s_setprio 1
	s_waitcnt lgkmcnt(0)
	v_mfma_f32_16x16x32_bf16 v[140:143], v[204:207], v[80:83], 0
	v_mfma_f32_16x16x32_bf16 v[80:83], v[228:231], v[80:83], 0
	v_mfma_f32_16x16x32_bf16 v[140:143], v[222:225], v[84:87], v[140:143]
	v_mfma_f32_16x16x32_bf16 v[80:83], v[232:235], v[84:87], v[80:83]
	v_mfma_f32_16x16x32_bf16 v[84:87], v[204:207], v[88:91], 0
	v_mfma_f32_16x16x32_bf16 v[88:91], v[228:231], v[88:91], 0
	v_mfma_f32_16x16x32_bf16 v[100:103], v[228:231], v[188:191], 0
	v_mfma_f32_16x16x32_bf16 v[104:107], v[204:207], v[196:199], 0
	v_mfma_f32_16x16x32_bf16 v[96:99], v[228:231], v[196:199], 0
	v_mfma_f32_16x16x32_bf16 v[84:87], v[222:225], v[92:95], v[84:87]
	v_mfma_f32_16x16x32_bf16 v[88:91], v[232:235], v[92:95], v[88:91]
	v_mfma_f32_16x16x32_bf16 v[92:95], v[204:207], v[188:191], 0
	v_mfma_f32_16x16x32_bf16 v[100:103], v[232:235], v[192:195], v[100:103]
	v_mfma_f32_16x16x32_bf16 v[128:131], v[222:225], v[200:203], v[104:107]
	v_mfma_f32_16x16x32_bf16 v[96:99], v[232:235], v[200:203], v[96:99]
	v_mfma_f32_16x16x32_bf16 v[92:95], v[222:225], v[192:195], v[92:95]
	s_setprio 0
	s_mov_b32 m0, s75
	v_lshl_add_u64 v[240:241], vcc, 0, v[144:145]
	s_barrier
	ds_read_b128 v[104:107], v220 offset:16384
	ds_read_b128 v[108:111], v220 offset:17408
	ds_read_b128 v[132:135], v220 offset:18432
	ds_read_b128 v[136:139], v220 offset:19456
	ds_read_b128 v[188:191], v220 offset:20480
	ds_read_b128 v[192:195], v220 offset:21504
	ds_read_b128 v[196:199], v220 offset:22528
	ds_read_b128 v[200:203], v220 offset:23552
	global_load_lds_dwordx4 v[240:241], off
	v_lshl_add_u64 v[242:243], vcc, 0, v[162:163]
	s_mov_b32 m0, s85
	s_nop 0
	global_load_lds_dwordx4 v[242:243], off
	s_barrier
	s_waitcnt lgkmcnt(0)
	s_setprio 1
	s_waitcnt lgkmcnt(0)
	v_mfma_f32_16x16x32_bf16 v[48:51], v[64:67], v[104:107], 0
	v_mfma_f32_16x16x32_bf16 v[20:23], v[72:75], v[104:107], 0
	v_mfma_f32_16x16x32_bf16 v[60:63], v[64:67], v[132:135], 0
	v_mfma_f32_16x16x32_bf16 v[28:31], v[72:75], v[132:135], 0
	v_mfma_f32_16x16x32_bf16 v[56:59], v[64:67], v[188:191], 0
	v_mfma_f32_16x16x32_bf16 v[16:19], v[72:75], v[188:191], 0
	v_mfma_f32_16x16x32_bf16 v[52:55], v[64:67], v[196:199], 0
	v_mfma_f32_16x16x32_bf16 v[24:27], v[72:75], v[196:199], 0
	v_mfma_f32_16x16x32_bf16 v[48:51], v[68:71], v[108:111], v[48:51]
	v_mfma_f32_16x16x32_bf16 v[20:23], v[76:79], v[108:111], v[20:23]
	v_mfma_f32_16x16x32_bf16 v[60:63], v[68:71], v[136:139], v[60:63]
	v_mfma_f32_16x16x32_bf16 v[28:31], v[76:79], v[136:139], v[28:31]
	v_mfma_f32_16x16x32_bf16 v[56:59], v[68:71], v[192:195], v[56:59]
	v_mfma_f32_16x16x32_bf16 v[16:19], v[76:79], v[192:195], v[16:19]
	v_mfma_f32_16x16x32_bf16 v[52:55], v[68:71], v[200:203], v[52:55]
	v_mfma_f32_16x16x32_bf16 v[24:27], v[76:79], v[200:203], v[24:27]
	s_setprio 0
	s_barrier
	s_add_u32 s56, s82, 0x40000
	s_addc_u32 s57, s83, 0
	s_add_i32 s27, s27, s74
	v_lshl_add_u64 v[64:65], s[56:57], 0, v[144:145]
	s_mov_b32 m0, s27
	s_nop 0
	global_load_lds_dwordx4 v[64:65], off
	v_lshl_add_u64 v[64:65], s[56:57], 0, v[162:163]
	s_add_i32 m0, s27, 0x2000
	s_nop 0
	global_load_lds_dwordx4 v[64:65], off
	s_waitcnt vmcnt(6)
	s_barrier
	s_setprio 1
	v_mfma_f32_16x16x32_bf16 v[44:47], v[204:207], v[104:107], 0
	v_mfma_f32_16x16x32_bf16 v[12:15], v[228:231], v[104:107], 0
	v_mfma_f32_16x16x32_bf16 v[40:43], v[204:207], v[132:135], 0
	v_mfma_f32_16x16x32_bf16 v[8:11], v[228:231], v[132:135], 0
	v_mfma_f32_16x16x32_bf16 v[36:39], v[204:207], v[188:191], 0
	v_mfma_f32_16x16x32_bf16 v[4:7], v[228:231], v[188:191], 0
	v_mfma_f32_16x16x32_bf16 v[32:35], v[204:207], v[196:199], 0
	v_mfma_f32_16x16x32_bf16 v[0:3], v[228:231], v[196:199], 0
	v_mfma_f32_16x16x32_bf16 v[44:47], v[222:225], v[108:111], v[44:47]
	v_mfma_f32_16x16x32_bf16 v[12:15], v[232:235], v[108:111], v[12:15]
	v_mfma_f32_16x16x32_bf16 v[40:43], v[222:225], v[136:139], v[40:43]
	v_mfma_f32_16x16x32_bf16 v[8:11], v[232:235], v[136:139], v[8:11]
	v_mfma_f32_16x16x32_bf16 v[36:39], v[222:225], v[192:195], v[36:39]
	v_mfma_f32_16x16x32_bf16 v[4:7], v[232:235], v[192:195], v[4:7]
	v_mfma_f32_16x16x32_bf16 v[32:35], v[222:225], v[200:203], v[32:35]
	v_mfma_f32_16x16x32_bf16 v[0:3], v[232:235], v[200:203], v[0:3]
	s_setprio 0
	s_add_i32 s27, 0, 0x18000
	v_add_u32_e32 v76, s27, v217
	s_barrier
	ds_read_b128 v[64:67], v76
	ds_read_b128 v[68:71], v76 offset:1024
	ds_read_b128 v[72:75], v76 offset:2048
	ds_read_b128 v[76:79], v76 offset:3072
	s_add_u32 s56, vcc_lo, 0x40000
	s_addc_u32 s57, vcc_hi, 0
	s_mov_b32 m0, s98
	v_lshl_add_u64 v[136:137], s[56:57], 0, v[144:145]
	ds_read_b128 v[104:107], v220 offset:32768
	ds_read_b128 v[108:111], v220 offset:33792
	ds_read_b128 v[132:135], v220 offset:34816
	ds_read_b128 v[188:191], v220 offset:35840
	ds_read_b128 v[192:195], v220 offset:36864
	ds_read_b128 v[196:199], v220 offset:37888
	ds_read_b128 v[200:203], v220 offset:38912
	ds_read_b128 v[204:207], v220 offset:39936
	global_load_lds_dwordx4 v[136:137], off
	v_lshl_add_u64 v[136:137], s[56:57], 0, v[162:163]
	s_mov_b32 m0, s29
	s_nop 0
	global_load_lds_dwordx4 v[136:137], off
	s_waitcnt lgkmcnt(8)
	s_barrier
	s_waitcnt lgkmcnt(0)
	s_setprio 1
	s_waitcnt lgkmcnt(0)
	v_mfma_f32_16x16x32_bf16 v[136:139], v[64:67], v[104:107], v[146:149]
	v_mfma_f32_16x16x32_bf16 v[146:149], v[68:71], v[108:111], v[136:139]
	v_mfma_f32_16x16x32_bf16 v[136:139], v[64:67], v[132:135], v[158:161]
	v_mfma_f32_16x16x32_bf16 v[158:161], v[68:71], v[188:191], v[136:139]
	v_mfma_f32_16x16x32_bf16 v[136:139], v[64:67], v[192:195], v[154:157]
	v_mfma_f32_16x16x32_bf16 v[116:119], v[72:75], v[104:107], v[116:119]
	v_mfma_f32_16x16x32_bf16 v[124:127], v[72:75], v[132:135], v[124:127]
	v_mfma_f32_16x16x32_bf16 v[154:157], v[68:71], v[196:199], v[136:139]
	v_mfma_f32_16x16x32_bf16 v[112:115], v[72:75], v[192:195], v[112:115]
	v_mfma_f32_16x16x32_bf16 v[136:139], v[64:67], v[200:203], v[150:153]
	v_mfma_f32_16x16x32_bf16 v[120:123], v[72:75], v[200:203], v[120:123]
	v_mfma_f32_16x16x32_bf16 v[116:119], v[76:79], v[108:111], v[116:119]
	v_mfma_f32_16x16x32_bf16 v[124:127], v[76:79], v[188:191], v[124:127]
	v_mfma_f32_16x16x32_bf16 v[112:115], v[76:79], v[196:199], v[112:115]
	v_mfma_f32_16x16x32_bf16 v[150:153], v[68:71], v[204:207], v[136:139]
	v_mfma_f32_16x16x32_bf16 v[120:123], v[76:79], v[204:207], v[120:123]
	s_setprio 0
	s_barrier
	s_add_i32 s58, 0, 0x1c000
	v_add_u32_e32 v136, s58, v217
	s_add_i32 s27, s27, s74
	ds_read_b128 v[222:225], v136
	ds_read_b128 v[228:231], v136 offset:1024
	ds_read_b128 v[232:235], v136 offset:2048
	ds_read_b128 v[236:239], v136 offset:3072
	v_lshl_add_u64 v[136:137], v[168:169], 0, s[18:19]
	s_mov_b32 m0, s27
	s_nop 0
	global_load_lds_dwordx4 v[136:137], off
	v_lshl_add_u64 v[136:137], v[176:177], 0, s[18:19]
	s_add_i32 m0, s27, 0x2000
	s_nop 0
	global_load_lds_dwordx4 v[136:137], off
	s_barrier
	s_waitcnt lgkmcnt(0)
	s_setprio 1
	s_waitcnt lgkmcnt(0)
	v_mfma_f32_16x16x32_bf16 v[136:139], v[222:225], v[104:107], v[140:143]
	v_mfma_f32_16x16x32_bf16 v[80:83], v[232:235], v[104:107], v[80:83]
	v_mfma_f32_16x16x32_bf16 v[140:143], v[228:231], v[108:111], v[136:139]
	v_mfma_f32_16x16x32_bf16 v[108:111], v[236:239], v[108:111], v[80:83]
	v_mfma_f32_16x16x32_bf16 v[80:83], v[222:225], v[132:135], v[84:87]
	v_mfma_f32_16x16x32_bf16 v[136:139], v[228:231], v[188:191], v[80:83]
	v_mfma_f32_16x16x32_bf16 v[80:83], v[232:235], v[132:135], v[88:91]
	v_mfma_f32_16x16x32_bf16 v[104:107], v[236:239], v[188:191], v[80:83]
	v_mfma_f32_16x16x32_bf16 v[80:83], v[222:225], v[192:195], v[92:95]
	v_mfma_f32_16x16x32_bf16 v[132:135], v[228:231], v[196:199], v[80:83]
	v_mfma_f32_16x16x32_bf16 v[80:83], v[232:235], v[192:195], v[100:103]
	v_mfma_f32_16x16x32_bf16 v[100:103], v[236:239], v[196:199], v[80:83]
	v_mfma_f32_16x16x32_bf16 v[80:83], v[222:225], v[200:203], v[128:131]
	v_mfma_f32_16x16x32_bf16 v[128:131], v[228:231], v[204:207], v[80:83]
	v_mfma_f32_16x16x32_bf16 v[80:83], v[232:235], v[200:203], v[96:99]
	v_mfma_f32_16x16x32_bf16 v[96:99], v[236:239], v[204:207], v[80:83]
	s_setprio 0
	s_mov_b32 m0, s31
	v_lshl_add_u64 v[168:169], v[240:241], 0, s[18:19]
	s_barrier
	s_nop 2
	ds_read_b128 v[80:83], v220 offset:49152
	ds_read_b128 v[84:87], v220 offset:50176
	ds_read_b128 v[88:91], v220 offset:51200
	ds_read_b128 v[92:95], v220 offset:52224
	ds_read_b128 v[188:191], v220 offset:53248
	ds_read_b128 v[192:195], v220 offset:54272
	ds_read_b128 v[196:199], v220 offset:55296
	ds_read_b128 v[200:203], v220 offset:56320
	global_load_lds_dwordx4 v[168:169], off
	v_lshl_add_u64 v[168:169], v[242:243], 0, s[18:19]
	s_mov_b32 m0, s34
	s_nop 0
	global_load_lds_dwordx4 v[168:169], off
	s_barrier
	s_waitcnt lgkmcnt(0)
	s_setprio 1
	s_waitcnt lgkmcnt(0)
	v_mfma_f32_16x16x32_bf16 v[48:51], v[64:67], v[80:83], v[48:51]
	v_mfma_f32_16x16x32_bf16 v[20:23], v[72:75], v[80:83], v[20:23]
	v_mfma_f32_16x16x32_bf16 v[60:63], v[64:67], v[88:91], v[60:63]
	v_mfma_f32_16x16x32_bf16 v[28:31], v[72:75], v[88:91], v[28:31]
	v_mfma_f32_16x16x32_bf16 v[56:59], v[64:67], v[188:191], v[56:59]
	v_mfma_f32_16x16x32_bf16 v[16:19], v[72:75], v[188:191], v[16:19]
	v_mfma_f32_16x16x32_bf16 v[52:55], v[64:67], v[196:199], v[52:55]
	v_mfma_f32_16x16x32_bf16 v[24:27], v[72:75], v[196:199], v[24:27]
	v_mfma_f32_16x16x32_bf16 v[48:51], v[68:71], v[84:87], v[48:51]
	v_mfma_f32_16x16x32_bf16 v[20:23], v[76:79], v[84:87], v[20:23]
	v_mfma_f32_16x16x32_bf16 v[60:63], v[68:71], v[92:95], v[60:63]
	v_mfma_f32_16x16x32_bf16 v[28:31], v[76:79], v[92:95], v[28:31]
	v_mfma_f32_16x16x32_bf16 v[56:59], v[68:71], v[192:195], v[56:59]
	v_mfma_f32_16x16x32_bf16 v[16:19], v[76:79], v[192:195], v[16:19]
	v_mfma_f32_16x16x32_bf16 v[52:55], v[68:71], v[200:203], v[52:55]
	v_mfma_f32_16x16x32_bf16 v[24:27], v[76:79], v[200:203], v[24:27]
	s_setprio 0
	s_barrier
	s_add_u32 s56, s82, 0x40080
	s_addc_u32 s57, s83, 0
	s_add_i32 s27, s58, s74
	v_lshl_add_u64 v[64:65], s[56:57], 0, v[144:145]
	s_mov_b32 m0, s27
	s_nop 0
	global_load_lds_dwordx4 v[64:65], off
	v_lshl_add_u64 v[64:65], s[56:57], 0, v[162:163]
	s_add_i32 m0, s27, 0x2000
	s_nop 0
	global_load_lds_dwordx4 v[64:65], off
	s_waitcnt vmcnt(6)
	s_barrier
	s_setprio 1
	v_mfma_f32_16x16x32_bf16 v[44:47], v[222:225], v[80:83], v[44:47]
	v_mfma_f32_16x16x32_bf16 v[12:15], v[232:235], v[80:83], v[12:15]
	v_mfma_f32_16x16x32_bf16 v[40:43], v[222:225], v[88:91], v[40:43]
	v_mfma_f32_16x16x32_bf16 v[8:11], v[232:235], v[88:91], v[8:11]
	v_mfma_f32_16x16x32_bf16 v[36:39], v[222:225], v[188:191], v[36:39]
	v_mfma_f32_16x16x32_bf16 v[4:7], v[232:235], v[188:191], v[4:7]
	v_mfma_f32_16x16x32_bf16 v[32:35], v[222:225], v[196:199], v[32:35]
	v_mfma_f32_16x16x32_bf16 v[0:3], v[232:235], v[196:199], v[0:3]
	v_mfma_f32_16x16x32_bf16 v[44:47], v[228:231], v[84:87], v[44:47]
	v_mfma_f32_16x16x32_bf16 v[12:15], v[236:239], v[84:87], v[12:15]
	v_mfma_f32_16x16x32_bf16 v[40:43], v[228:231], v[92:95], v[40:43]
	v_mfma_f32_16x16x32_bf16 v[8:11], v[236:239], v[92:95], v[8:11]
	v_mfma_f32_16x16x32_bf16 v[36:39], v[228:231], v[192:195], v[36:39]
	v_mfma_f32_16x16x32_bf16 v[4:7], v[236:239], v[192:195], v[4:7]
	v_mfma_f32_16x16x32_bf16 v[32:35], v[228:231], v[200:203], v[32:35]
	v_mfma_f32_16x16x32_bf16 v[0:3], v[236:239], v[200:203], v[0:3]
	s_setprio 0
	s_add_i32 s37, s37, 2
	s_add_u32 s86, s86, 0x100
	s_addc_u32 s87, s87, 0
	s_add_u32 s33, s33, 0x100
	s_addc_u32 s36, s36, 0
	s_cmp_gt_u32 s37, 13
	s_barrier

.LBB0_195:
	s_add_u32 s42, s78, 0x80
	s_addc_u32 s43, s79, 0
	s_add_u32 s33, s44, 0x100
	s_addc_u32 s37, s45, 0
	s_mov_b32 s27, 0
	s_waitcnt lgkmcnt(0)
	s_add_i32 s56, s27, 2
	s_add_u32 s44, s42, 0x80
	s_addc_u32 s45, s43, 0
	s_add_i32 s57, 0, 0x10000
	v_add_u32_e32 v140, s57, v207
	ds_read_b128 v[128:131], v140
	ds_read_b128 v[132:135], v140 offset:1024
	ds_read_b128 v[136:139], v140 offset:2048
	ds_read_b128 v[140:143], v140 offset:3072
	s_cmp_eq_u32 s82, s27
	s_cselect_b32 s45, s77, s45
	s_cselect_b32 s44, s76, s44
	s_cselect_b32 s79, s1, s37
	s_cselect_b32 s78, s0, s33
	v_lshl_add_u64 v[176:177], s[42:43], 0, v[190:191]
	s_add_i32 m0, s85, 0xc000
	ds_read_b128 v[146:149], v217
	ds_read_b128 v[150:153], v217 offset:1024
	ds_read_b128 v[154:157], v217 offset:2048
	ds_read_b128 v[158:161], v217 offset:3072
	ds_read_b128 v[162:165], v217 offset:4096
	ds_read_b128 v[166:169], v217 offset:5120
	ds_read_b128 v[194:197], v217 offset:6144
	ds_read_b128 v[198:201], v217 offset:7168
	global_load_lds_dwordx4 v[176:177], off
	v_lshl_add_u64 v[176:177], s[42:43], 0, v[192:193]
	s_add_i32 m0, s85, 0xe000
	s_nop 0
	global_load_lds_dwordx4 v[176:177], off
	s_waitcnt lgkmcnt(8)
	s_barrier
	s_waitcnt lgkmcnt(0)
	s_setprio 1
	s_waitcnt lgkmcnt(0)
	v_mfma_f32_16x16x32_bf16 v[124:127], v[128:131], v[146:149], 0
	v_mfma_f32_16x16x32_bf16 v[120:123], v[136:139], v[146:149], 0
	v_mfma_f32_16x16x32_bf16 v[108:111], v[128:131], v[154:157], 0
	v_mfma_f32_16x16x32_bf16 v[104:107], v[136:139], v[154:157], 0
	v_mfma_f32_16x16x32_bf16 v[92:95], v[128:131], v[162:165], 0
	v_mfma_f32_16x16x32_bf16 v[88:91], v[136:139], v[162:165], 0
	v_mfma_f32_16x16x32_bf16 v[76:79], v[128:131], v[194:197], 0
	v_mfma_f32_16x16x32_bf16 v[72:75], v[136:139], v[194:197], 0
	v_mfma_f32_16x16x32_bf16 v[124:127], v[132:135], v[150:153], v[124:127]
	v_mfma_f32_16x16x32_bf16 v[120:123], v[140:143], v[150:153], v[120:123]
	v_mfma_f32_16x16x32_bf16 v[108:111], v[132:135], v[158:161], v[108:111]
	v_mfma_f32_16x16x32_bf16 v[104:107], v[140:143], v[158:161], v[104:107]
	v_mfma_f32_16x16x32_bf16 v[92:95], v[132:135], v[166:169], v[92:95]
	v_mfma_f32_16x16x32_bf16 v[88:91], v[140:143], v[166:169], v[88:91]
	v_mfma_f32_16x16x32_bf16 v[76:79], v[132:135], v[198:201], v[76:79]
	v_mfma_f32_16x16x32_bf16 v[72:75], v[140:143], v[198:201], v[72:75]
	s_setprio 0
	s_barrier
	s_add_i32 s27, 0, 0x14000
	v_add_u32_e32 v176, s27, v207
	s_add_i32 s57, s57, s84
	ds_read_b128 v[202:205], v176
	ds_read_b128 v[218:221], v176 offset:1024
	ds_read_b128 v[222:225], v176 offset:2048
	ds_read_b128 v[228:231], v176 offset:3072
	v_lshl_add_u64 v[176:177], s[78:79], 0, v[144:145]
	s_mov_b32 m0, s57
	v_lshl_add_u64 v[232:233], s[78:79], 0, v[188:189]
	global_load_lds_dwordx4 v[176:177], off
	s_add_i32 m0, s57, 0x2000
	s_nop 0
	global_load_lds_dwordx4 v[232:233], off
	s_barrier
	s_waitcnt lgkmcnt(0)
	s_setprio 1
	s_waitcnt lgkmcnt(0)
	v_mfma_f32_16x16x32_bf16 v[116:119], v[202:205], v[146:149], 0
	v_mfma_f32_16x16x32_bf16 v[112:115], v[222:225], v[146:149], 0
	v_mfma_f32_16x16x32_bf16 v[100:103], v[202:205], v[154:157], 0
	v_mfma_f32_16x16x32_bf16 v[96:99], v[222:225], v[154:157], 0
	v_mfma_f32_16x16x32_bf16 v[84:87], v[202:205], v[162:165], 0
	v_mfma_f32_16x16x32_bf16 v[80:83], v[222:225], v[162:165], 0
	v_mfma_f32_16x16x32_bf16 v[68:71], v[202:205], v[194:197], 0
	v_mfma_f32_16x16x32_bf16 v[64:67], v[222:225], v[194:197], 0
	v_mfma_f32_16x16x32_bf16 v[116:119], v[218:221], v[150:153], v[116:119]
	v_mfma_f32_16x16x32_bf16 v[112:115], v[228:231], v[150:153], v[112:115]
	v_mfma_f32_16x16x32_bf16 v[100:103], v[218:221], v[158:161], v[100:103]
	v_mfma_f32_16x16x32_bf16 v[96:99], v[228:231], v[158:161], v[96:99]
	v_mfma_f32_16x16x32_bf16 v[84:87], v[218:221], v[166:169], v[84:87]
	v_mfma_f32_16x16x32_bf16 v[80:83], v[228:231], v[166:169], v[80:83]
	v_mfma_f32_16x16x32_bf16 v[68:71], v[218:221], v[198:201], v[68:71]
	v_mfma_f32_16x16x32_bf16 v[64:67], v[228:231], v[198:201], v[64:67]
	s_setprio 0
	s_mov_b32 m0, s85
	v_lshl_add_u64 v[234:235], s[44:45], 0, v[144:145]
	s_barrier
	ds_read_b128 v[146:149], v217 offset:16384
	ds_read_b128 v[150:153], v217 offset:17408
	ds_read_b128 v[154:157], v217 offset:18432
	ds_read_b128 v[158:161], v217 offset:19456
	ds_read_b128 v[162:165], v217 offset:20480
	ds_read_b128 v[166:169], v217 offset:21504
	ds_read_b128 v[194:197], v217 offset:22528
	ds_read_b128 v[198:201], v217 offset:23552
	global_load_lds_dwordx4 v[234:235], off
	v_lshl_add_u64 v[236:237], s[44:45], 0, v[188:189]
	s_mov_b32 m0, s86
	s_nop 0
	global_load_lds_dwordx4 v[236:237], off
	s_barrier
	s_waitcnt lgkmcnt(0)
	s_setprio 1
	s_waitcnt lgkmcnt(0)
	v_mfma_f32_16x16x32_bf16 v[60:63], v[128:131], v[146:149], 0
	v_mfma_f32_16x16x32_bf16 v[56:59], v[136:139], v[146:149], 0
	v_mfma_f32_16x16x32_bf16 v[44:47], v[128:131], v[154:157], 0
	v_mfma_f32_16x16x32_bf16 v[40:43], v[136:139], v[154:157], 0
	v_mfma_f32_16x16x32_bf16 v[28:31], v[128:131], v[162:165], 0
	v_mfma_f32_16x16x32_bf16 v[24:27], v[136:139], v[162:165], 0
	v_mfma_f32_16x16x32_bf16 v[12:15], v[128:131], v[194:197], 0
	v_mfma_f32_16x16x32_bf16 v[8:11], v[136:139], v[194:197], 0
	v_mfma_f32_16x16x32_bf16 v[60:63], v[132:135], v[150:153], v[60:63]
	v_mfma_f32_16x16x32_bf16 v[56:59], v[140:143], v[150:153], v[56:59]
	v_mfma_f32_16x16x32_bf16 v[44:47], v[132:135], v[158:161], v[44:47]
	v_mfma_f32_16x16x32_bf16 v[40:43], v[140:143], v[158:161], v[40:43]
	v_mfma_f32_16x16x32_bf16 v[28:31], v[132:135], v[166:169], v[28:31]
	v_mfma_f32_16x16x32_bf16 v[24:27], v[140:143], v[166:169], v[24:27]
	v_mfma_f32_16x16x32_bf16 v[12:15], v[132:135], v[198:201], v[12:15]
	v_mfma_f32_16x16x32_bf16 v[8:11], v[140:143], v[198:201], v[8:11]
	s_setprio 0
	s_barrier
	s_add_u32 s58, s78, s98
	s_addc_u32 s59, s79, 0
	s_add_i32 s27, s27, s84
	v_lshl_add_u64 v[238:239], s[58:59], 0, v[144:145]
	s_mov_b32 m0, s27
	v_lshl_add_u64 v[240:241], s[58:59], 0, v[188:189]
	global_load_lds_dwordx4 v[238:239], off
	s_add_i32 m0, s27, 0x2000
	s_nop 0
	global_load_lds_dwordx4 v[240:241], off
	s_waitcnt vmcnt(6)
	s_barrier
	s_setprio 1
	v_mfma_f32_16x16x32_bf16 v[52:55], v[202:205], v[146:149], 0
	v_mfma_f32_16x16x32_bf16 v[48:51], v[222:225], v[146:149], 0
	v_mfma_f32_16x16x32_bf16 v[36:39], v[202:205], v[154:157], 0
	v_mfma_f32_16x16x32_bf16 v[32:35], v[222:225], v[154:157], 0
	v_mfma_f32_16x16x32_bf16 v[20:23], v[202:205], v[162:165], 0
	v_mfma_f32_16x16x32_bf16 v[16:19], v[222:225], v[162:165], 0
	v_mfma_f32_16x16x32_bf16 v[4:7], v[202:205], v[194:197], 0
	v_mfma_f32_16x16x32_bf16 v[0:3], v[222:225], v[194:197], 0
	v_mfma_f32_16x16x32_bf16 v[52:55], v[218:221], v[150:153], v[52:55]
	v_mfma_f32_16x16x32_bf16 v[48:51], v[228:231], v[150:153], v[48:51]
	v_mfma_f32_16x16x32_bf16 v[36:39], v[218:221], v[158:161], v[36:39]
	v_mfma_f32_16x16x32_bf16 v[32:35], v[228:231], v[158:161], v[32:35]
	v_mfma_f32_16x16x32_bf16 v[20:23], v[218:221], v[166:169], v[20:23]
	v_mfma_f32_16x16x32_bf16 v[16:19], v[228:231], v[166:169], v[16:19]
	v_mfma_f32_16x16x32_bf16 v[4:7], v[218:221], v[198:201], v[4:7]
	v_mfma_f32_16x16x32_bf16 v[0:3], v[228:231], v[198:201], v[0:3]
	s_setprio 0
	s_add_i32 s27, 0, 0x18000
	v_add_u32_e32 v140, s27, v207
	s_barrier
	ds_read_b128 v[128:131], v140
	ds_read_b128 v[132:135], v140 offset:1024
	ds_read_b128 v[136:139], v140 offset:2048
	ds_read_b128 v[140:143], v140 offset:3072
	s_add_u32 s44, s44, s98
	s_addc_u32 s45, s45, 0
	s_mov_b32 m0, s87
	v_lshl_add_u64 v[202:203], s[44:45], 0, v[144:145]
	ds_read_b128 v[146:149], v217 offset:32768
	ds_read_b128 v[150:153], v217 offset:33792
	ds_read_b128 v[154:157], v217 offset:34816
	ds_read_b128 v[158:161], v217 offset:35840
	ds_read_b128 v[162:165], v217 offset:36864
	ds_read_b128 v[166:169], v217 offset:37888
	ds_read_b128 v[194:197], v217 offset:38912
	ds_read_b128 v[198:201], v217 offset:39936
	global_load_lds_dwordx4 v[202:203], off
	v_lshl_add_u64 v[202:203], s[44:45], 0, v[188:189]
	s_mov_b32 m0, s80
	s_nop 0
	global_load_lds_dwordx4 v[202:203], off
	s_waitcnt lgkmcnt(8)
	s_barrier
	s_waitcnt lgkmcnt(0)
	s_setprio 1
	s_waitcnt lgkmcnt(0)
	v_mfma_f32_16x16x32_bf16 v[124:127], v[128:131], v[146:149], v[124:127]
	v_mfma_f32_16x16x32_bf16 v[120:123], v[136:139], v[146:149], v[120:123]
	v_mfma_f32_16x16x32_bf16 v[108:111], v[128:131], v[154:157], v[108:111]
	v_mfma_f32_16x16x32_bf16 v[104:107], v[136:139], v[154:157], v[104:107]
	v_mfma_f32_16x16x32_bf16 v[92:95], v[128:131], v[162:165], v[92:95]
	v_mfma_f32_16x16x32_bf16 v[88:91], v[136:139], v[162:165], v[88:91]
	v_mfma_f32_16x16x32_bf16 v[76:79], v[128:131], v[194:197], v[76:79]
	v_mfma_f32_16x16x32_bf16 v[72:75], v[136:139], v[194:197], v[72:75]
	v_mfma_f32_16x16x32_bf16 v[124:127], v[132:135], v[150:153], v[124:127]
	v_mfma_f32_16x16x32_bf16 v[120:123], v[140:143], v[150:153], v[120:123]
	v_mfma_f32_16x16x32_bf16 v[108:111], v[132:135], v[158:161], v[108:111]
	v_mfma_f32_16x16x32_bf16 v[104:107], v[140:143], v[158:161], v[104:107]
	v_mfma_f32_16x16x32_bf16 v[92:95], v[132:135], v[166:169], v[92:95]
	v_mfma_f32_16x16x32_bf16 v[88:91], v[140:143], v[166:169], v[88:91]
	v_mfma_f32_16x16x32_bf16 v[76:79], v[132:135], v[198:201], v[76:79]
	v_mfma_f32_16x16x32_bf16 v[72:75], v[140:143], v[198:201], v[72:75]
	s_setprio 0
	s_barrier
	s_add_i32 s44, 0, 0x1c000
	s_add_i32 s27, s27, s84
	v_add_u32_e32 v228, s44, v207
	v_lshl_add_u64 v[176:177], v[176:177], 0, s[18:19]
	s_mov_b32 m0, s27
	ds_read_b128 v[202:205], v228
	ds_read_b128 v[218:221], v228 offset:1024
	ds_read_b128 v[222:225], v228 offset:2048
	ds_read_b128 v[228:231], v228 offset:3072
	global_load_lds_dwordx4 v[176:177], off
	v_lshl_add_u64 v[176:177], v[232:233], 0, s[18:19]
	s_add_i32 m0, s27, 0x2000
	s_nop 0
	global_load_lds_dwordx4 v[176:177], off
	s_barrier
	s_waitcnt lgkmcnt(0)
	s_setprio 1
	s_waitcnt lgkmcnt(0)
	v_mfma_f32_16x16x32_bf16 v[116:119], v[202:205], v[146:149], v[116:119]
	v_mfma_f32_16x16x32_bf16 v[112:115], v[222:225], v[146:149], v[112:115]
	v_mfma_f32_16x16x32_bf16 v[100:103], v[202:205], v[154:157], v[100:103]
	v_mfma_f32_16x16x32_bf16 v[96:99], v[222:225], v[154:157], v[96:99]
	v_mfma_f32_16x16x32_bf16 v[84:87], v[202:205], v[162:165], v[84:87]
	v_mfma_f32_16x16x32_bf16 v[80:83], v[222:225], v[162:165], v[80:83]
	v_mfma_f32_16x16x32_bf16 v[68:71], v[202:205], v[194:197], v[68:71]
	v_mfma_f32_16x16x32_bf16 v[64:67], v[222:225], v[194:197], v[64:67]
	v_mfma_f32_16x16x32_bf16 v[116:119], v[218:221], v[150:153], v[116:119]
	v_mfma_f32_16x16x32_bf16 v[112:115], v[228:231], v[150:153], v[112:115]
	v_mfma_f32_16x16x32_bf16 v[100:103], v[218:221], v[158:161], v[100:103]
	v_mfma_f32_16x16x32_bf16 v[96:99], v[228:231], v[158:161], v[96:99]
	v_mfma_f32_16x16x32_bf16 v[84:87], v[218:221], v[166:169], v[84:87]
	v_mfma_f32_16x16x32_bf16 v[80:83], v[228:231], v[166:169], v[80:83]
	v_mfma_f32_16x16x32_bf16 v[68:71], v[218:221], v[198:201], v[68:71]
	v_mfma_f32_16x16x32_bf16 v[64:67], v[228:231], v[198:201], v[64:67]
	s_setprio 0
	s_mov_b32 m0, s30
	v_lshl_add_u64 v[176:177], v[234:235], 0, s[18:19]
	s_barrier
	ds_read_b128 v[146:149], v217 offset:49152
	ds_read_b128 v[150:153], v217 offset:50176
	ds_read_b128 v[154:157], v217 offset:51200
	ds_read_b128 v[158:161], v217 offset:52224
	ds_read_b128 v[162:165], v217 offset:53248
	ds_read_b128 v[166:169], v217 offset:54272
	ds_read_b128 v[194:197], v217 offset:55296
	ds_read_b128 v[198:201], v217 offset:56320
	global_load_lds_dwordx4 v[176:177], off
	v_lshl_add_u64 v[176:177], v[236:237], 0, s[18:19]
	s_mov_b32 m0, s31
	s_nop 0
	global_load_lds_dwordx4 v[176:177], off
	s_barrier
	s_waitcnt lgkmcnt(0)
	s_setprio 1
	s_waitcnt lgkmcnt(0)
	v_mfma_f32_16x16x32_bf16 v[60:63], v[128:131], v[146:149], v[60:63]
	v_mfma_f32_16x16x32_bf16 v[56:59], v[136:139], v[146:149], v[56:59]
	v_mfma_f32_16x16x32_bf16 v[44:47], v[128:131], v[154:157], v[44:47]
	v_mfma_f32_16x16x32_bf16 v[40:43], v[136:139], v[154:157], v[40:43]
	v_mfma_f32_16x16x32_bf16 v[28:31], v[128:131], v[162:165], v[28:31]
	v_mfma_f32_16x16x32_bf16 v[24:27], v[136:139], v[162:165], v[24:27]
	v_mfma_f32_16x16x32_bf16 v[12:15], v[128:131], v[194:197], v[12:15]
	v_mfma_f32_16x16x32_bf16 v[8:11], v[136:139], v[194:197], v[8:11]
	v_mfma_f32_16x16x32_bf16 v[60:63], v[132:135], v[150:153], v[60:63]
	v_mfma_f32_16x16x32_bf16 v[56:59], v[140:143], v[150:153], v[56:59]
	v_mfma_f32_16x16x32_bf16 v[44:47], v[132:135], v[158:161], v[44:47]
	v_mfma_f32_16x16x32_bf16 v[40:43], v[140:143], v[158:161], v[40:43]
	v_mfma_f32_16x16x32_bf16 v[28:31], v[132:135], v[166:169], v[28:31]
	v_mfma_f32_16x16x32_bf16 v[24:27], v[140:143], v[166:169], v[24:27]
	v_mfma_f32_16x16x32_bf16 v[12:15], v[132:135], v[198:201], v[12:15]
	v_mfma_f32_16x16x32_bf16 v[8:11], v[140:143], v[198:201], v[8:11]
	s_setprio 0
	s_barrier
	s_add_i32 s27, s44, s84
	v_lshl_add_u64 v[128:129], v[238:239], 0, s[18:19]
	s_mov_b32 m0, s27
	s_nop 0
	global_load_lds_dwordx4 v[128:129], off
	v_lshl_add_u64 v[128:129], v[240:241], 0, s[18:19]
	s_add_i32 m0, s27, 0x2000
	s_nop 0
	global_load_lds_dwordx4 v[128:129], off
	s_waitcnt vmcnt(6)
	s_barrier
	s_setprio 1
	v_mfma_f32_16x16x32_bf16 v[52:55], v[202:205], v[146:149], v[52:55]
	v_mfma_f32_16x16x32_bf16 v[48:51], v[222:225], v[146:149], v[48:51]
	v_mfma_f32_16x16x32_bf16 v[36:39], v[202:205], v[154:157], v[36:39]
	v_mfma_f32_16x16x32_bf16 v[32:35], v[222:225], v[154:157], v[32:35]
	v_mfma_f32_16x16x32_bf16 v[20:23], v[202:205], v[162:165], v[20:23]
	v_mfma_f32_16x16x32_bf16 v[16:19], v[222:225], v[162:165], v[16:19]
	v_mfma_f32_16x16x32_bf16 v[4:7], v[202:205], v[194:197], v[4:7]
	v_mfma_f32_16x16x32_bf16 v[0:3], v[222:225], v[194:197], v[0:3]
	v_mfma_f32_16x16x32_bf16 v[52:55], v[218:221], v[150:153], v[52:55]
	v_mfma_f32_16x16x32_bf16 v[48:51], v[228:231], v[150:153], v[48:51]
	v_mfma_f32_16x16x32_bf16 v[36:39], v[218:221], v[158:161], v[36:39]
	v_mfma_f32_16x16x32_bf16 v[32:35], v[228:231], v[158:161], v[32:35]
	v_mfma_f32_16x16x32_bf16 v[20:23], v[218:221], v[166:169], v[20:23]
	v_mfma_f32_16x16x32_bf16 v[16:19], v[228:231], v[166:169], v[16:19]
	v_mfma_f32_16x16x32_bf16 v[4:7], v[218:221], v[198:201], v[4:7]
	v_mfma_f32_16x16x32_bf16 v[0:3], v[228:231], v[198:201], v[0:3]
	s_setprio 0
	s_add_u32 s42, s42, 0x100
	s_addc_u32 s43, s43, 0
	s_add_u32 s33, s33, 0x100
	s_addc_u32 s37, s37, 0
	s_cmp_ge_u32 s56, s34
	s_mov_b32 s27, s56
	s_barrier

.LBB0_325:
	s_ashr_i32 s93, s92, 31
	s_lshl_b64 s[30:31], s[92:93], 19
	s_add_u32 s94, s54, s30
	v_cmp_lt_i64_e32 vcc, s[50:51], v[186:187]
	s_addc_u32 s95, s55, s31
	s_and_b64 s[30:31], vcc, exec
	s_cselect_b32 s1, s95, s53
	s_cselect_b32 s11, s94, s52
	s_ashr_i32 s9, s8, 31
	s_lshl_b64 s[30:31], s[8:9], 19
	s_add_u32 s28, s80, s30
	s_addc_u32 s29, s78, s31
	s_and_b64 s[30:31], vcc, exec
	s_cselect_b32 s25, s29, s73
	s_cselect_b32 s30, s28, s72
	s_add_u32 s52, s52, 0x40080
	s_addc_u32 s53, s53, 0
	s_add_u32 s31, s72, 0x100
	s_addc_u32 s33, s73, 0
	s_mov_b32 s34, -2
	s_add_u32 s27, s52, 0xfffc0080
	s_addc_u32 s35, s53, -1
	s_add_i32 s36, 0, 0x10000
	v_add_u32_e32 v140, s36, v216
	ds_read_b128 v[128:131], v140
	ds_read_b128 v[132:135], v140 offset:1024
	ds_read_b128 v[136:139], v140 offset:2048
	ds_read_b128 v[140:143], v140 offset:3072
	s_cmp_eq_u32 s34, 12
	s_cselect_b32 s75, s1, s35
	s_cselect_b32 s74, s11, s27
	s_cselect_b32 s73, s25, s33
	s_cselect_b32 s72, s30, s31
	v_lshl_add_u64 v[168:169], s[52:53], 0, v[152:153]
	s_add_i32 m0, s83, 0xc000
	ds_read_b128 v[156:159], v217
	ds_read_b128 v[160:163], v217 offset:1024
	ds_read_b128 v[164:167], v217 offset:2048
	ds_read_b128 v[188:191], v217 offset:3072
	ds_read_b128 v[192:195], v217 offset:4096
	ds_read_b128 v[196:199], v217 offset:5120
	ds_read_b128 v[200:203], v217 offset:6144
	ds_read_b128 v[204:207], v217 offset:7168
	global_load_lds_dwordx4 v[168:169], off
	v_lshl_add_u64 v[168:169], s[52:53], 0, v[154:155]
	s_add_i32 m0, s83, 0xe000
	s_nop 0
	global_load_lds_dwordx4 v[168:169], off
	s_waitcnt lgkmcnt(8)
	s_barrier
	s_waitcnt lgkmcnt(0)
	s_setprio 1
	s_waitcnt lgkmcnt(0)
	v_mfma_f32_16x16x32_bf16 v[124:127], v[128:131], v[156:159], 0
	v_mfma_f32_16x16x32_bf16 v[120:123], v[136:139], v[156:159], 0
	v_mfma_f32_16x16x32_bf16 v[108:111], v[128:131], v[164:167], 0
	v_mfma_f32_16x16x32_bf16 v[104:107], v[136:139], v[164:167], 0
	v_mfma_f32_16x16x32_bf16 v[92:95], v[128:131], v[192:195], 0
	v_mfma_f32_16x16x32_bf16 v[88:91], v[136:139], v[192:195], 0
	v_mfma_f32_16x16x32_bf16 v[76:79], v[128:131], v[200:203], 0
	v_mfma_f32_16x16x32_bf16 v[72:75], v[136:139], v[200:203], 0
	v_mfma_f32_16x16x32_bf16 v[124:127], v[132:135], v[160:163], v[124:127]
	v_mfma_f32_16x16x32_bf16 v[120:123], v[140:143], v[160:163], v[120:123]
	v_mfma_f32_16x16x32_bf16 v[108:111], v[132:135], v[188:191], v[108:111]
	v_mfma_f32_16x16x32_bf16 v[104:107], v[140:143], v[188:191], v[104:107]
	v_mfma_f32_16x16x32_bf16 v[92:95], v[132:135], v[196:199], v[92:95]
	v_mfma_f32_16x16x32_bf16 v[88:91], v[140:143], v[196:199], v[88:91]
	v_mfma_f32_16x16x32_bf16 v[76:79], v[132:135], v[204:207], v[76:79]
	v_mfma_f32_16x16x32_bf16 v[72:75], v[140:143], v[204:207], v[72:75]
	s_setprio 0
	s_barrier
	s_add_i32 s27, 0, 0x14000
	s_add_i32 s35, s36, s81
	v_add_u32_e32 v144, s27, v216
	v_lshl_add_u64 v[168:169], s[72:73], 0, v[148:149]
	s_mov_b32 m0, s35
	ds_read_b128 v[220:223], v144
	ds_read_b128 v[228:231], v144 offset:1024
	ds_read_b128 v[232:235], v144 offset:2048
	ds_read_b128 v[236:239], v144 offset:3072
	global_load_lds_dwordx4 v[168:169], off
	v_lshl_add_u64 v[176:177], s[72:73], 0, v[146:147]
	s_add_i32 m0, s35, 0x2000
	s_nop 0
	global_load_lds_dwordx4 v[176:177], off
	s_barrier
	s_waitcnt lgkmcnt(0)
	s_setprio 1
	s_waitcnt lgkmcnt(0)
	v_mfma_f32_16x16x32_bf16 v[116:119], v[220:223], v[156:159], 0
	v_mfma_f32_16x16x32_bf16 v[112:115], v[232:235], v[156:159], 0
	v_mfma_f32_16x16x32_bf16 v[100:103], v[220:223], v[164:167], 0
	v_mfma_f32_16x16x32_bf16 v[96:99], v[232:235], v[164:167], 0
	v_mfma_f32_16x16x32_bf16 v[84:87], v[220:223], v[192:195], 0
	v_mfma_f32_16x16x32_bf16 v[80:83], v[232:235], v[192:195], 0
	v_mfma_f32_16x16x32_bf16 v[68:71], v[220:223], v[200:203], 0
	v_mfma_f32_16x16x32_bf16 v[64:67], v[232:235], v[200:203], 0
	v_mfma_f32_16x16x32_bf16 v[116:119], v[228:231], v[160:163], v[116:119]
	v_mfma_f32_16x16x32_bf16 v[112:115], v[236:239], v[160:163], v[112:115]
	v_mfma_f32_16x16x32_bf16 v[100:103], v[228:231], v[188:191], v[100:103]
	v_mfma_f32_16x16x32_bf16 v[96:99], v[236:239], v[188:191], v[96:99]
	v_mfma_f32_16x16x32_bf16 v[84:87], v[228:231], v[196:199], v[84:87]
	v_mfma_f32_16x16x32_bf16 v[80:83], v[236:239], v[196:199], v[80:83]
	v_mfma_f32_16x16x32_bf16 v[68:71], v[228:231], v[204:207], v[68:71]
	v_mfma_f32_16x16x32_bf16 v[64:67], v[236:239], v[204:207], v[64:67]
	s_setprio 0
	s_mov_b32 m0, s83
	v_lshl_add_u64 v[224:225], s[74:75], 0, v[148:149]
	s_barrier
	ds_read_b128 v[156:159], v217 offset:16384
	ds_read_b128 v[160:163], v217 offset:17408
	ds_read_b128 v[164:167], v217 offset:18432
	ds_read_b128 v[188:191], v217 offset:19456
	ds_read_b128 v[192:195], v217 offset:20480
	ds_read_b128 v[196:199], v217 offset:21504
	ds_read_b128 v[200:203], v217 offset:22528
	ds_read_b128 v[204:207], v217 offset:23552
	global_load_lds_dwordx4 v[224:225], off
	v_lshl_add_u64 v[240:241], s[74:75], 0, v[146:147]
	s_mov_b32 m0, s84
	s_nop 0
	global_load_lds_dwordx4 v[240:241], off
	s_barrier
	s_waitcnt lgkmcnt(0)
	s_setprio 1
	s_waitcnt lgkmcnt(0)
	v_mfma_f32_16x16x32_bf16 v[60:63], v[128:131], v[156:159], 0
	v_mfma_f32_16x16x32_bf16 v[56:59], v[136:139], v[156:159], 0
	v_mfma_f32_16x16x32_bf16 v[44:47], v[128:131], v[164:167], 0
	v_mfma_f32_16x16x32_bf16 v[40:43], v[136:139], v[164:167], 0
	v_mfma_f32_16x16x32_bf16 v[28:31], v[128:131], v[192:195], 0
	v_mfma_f32_16x16x32_bf16 v[24:27], v[136:139], v[192:195], 0
	v_mfma_f32_16x16x32_bf16 v[12:15], v[128:131], v[200:203], 0
	v_mfma_f32_16x16x32_bf16 v[8:11], v[136:139], v[200:203], 0
	v_mfma_f32_16x16x32_bf16 v[60:63], v[132:135], v[160:163], v[60:63]
	v_mfma_f32_16x16x32_bf16 v[56:59], v[140:143], v[160:163], v[56:59]
	v_mfma_f32_16x16x32_bf16 v[44:47], v[132:135], v[188:191], v[44:47]
	v_mfma_f32_16x16x32_bf16 v[40:43], v[140:143], v[188:191], v[40:43]
	v_mfma_f32_16x16x32_bf16 v[28:31], v[132:135], v[196:199], v[28:31]
	v_mfma_f32_16x16x32_bf16 v[24:27], v[140:143], v[196:199], v[24:27]
	v_mfma_f32_16x16x32_bf16 v[12:15], v[132:135], v[204:207], v[12:15]
	v_mfma_f32_16x16x32_bf16 v[8:11], v[140:143], v[204:207], v[8:11]
	s_setprio 0
	s_barrier
	s_add_u32 s36, s72, 0x40000
	s_addc_u32 s37, s73, 0
	s_add_i32 s27, s27, s81
	v_lshl_add_u64 v[128:129], s[36:37], 0, v[148:149]
	s_mov_b32 m0, s27
	s_nop 0
	global_load_lds_dwordx4 v[128:129], off
	v_lshl_add_u64 v[128:129], s[36:37], 0, v[146:147]
	s_add_i32 m0, s27, 0x2000
	s_nop 0
	global_load_lds_dwordx4 v[128:129], off
	s_waitcnt vmcnt(6)
	s_barrier
	s_setprio 1
	v_mfma_f32_16x16x32_bf16 v[52:55], v[220:223], v[156:159], 0
	v_mfma_f32_16x16x32_bf16 v[48:51], v[232:235], v[156:159], 0
	v_mfma_f32_16x16x32_bf16 v[36:39], v[220:223], v[164:167], 0
	v_mfma_f32_16x16x32_bf16 v[32:35], v[232:235], v[164:167], 0
	v_mfma_f32_16x16x32_bf16 v[20:23], v[220:223], v[192:195], 0
	v_mfma_f32_16x16x32_bf16 v[16:19], v[232:235], v[192:195], 0
	v_mfma_f32_16x16x32_bf16 v[4:7], v[220:223], v[200:203], 0
	v_mfma_f32_16x16x32_bf16 v[0:3], v[232:235], v[200:203], 0
	v_mfma_f32_16x16x32_bf16 v[52:55], v[228:231], v[160:163], v[52:55]
	v_mfma_f32_16x16x32_bf16 v[48:51], v[236:239], v[160:163], v[48:51]
	v_mfma_f32_16x16x32_bf16 v[36:39], v[228:231], v[188:191], v[36:39]
	v_mfma_f32_16x16x32_bf16 v[32:35], v[236:239], v[188:191], v[32:35]
	v_mfma_f32_16x16x32_bf16 v[20:23], v[228:231], v[196:199], v[20:23]
	v_mfma_f32_16x16x32_bf16 v[16:19], v[236:239], v[196:199], v[16:19]
	v_mfma_f32_16x16x32_bf16 v[4:7], v[228:231], v[204:207], v[4:7]
	v_mfma_f32_16x16x32_bf16 v[0:3], v[236:239], v[204:207], v[0:3]
	s_setprio 0
	s_add_i32 s27, 0, 0x18000
	v_add_u32_e32 v140, s27, v216
	s_barrier
	ds_read_b128 v[128:131], v140
	ds_read_b128 v[132:135], v140 offset:1024
	ds_read_b128 v[136:139], v140 offset:2048
	ds_read_b128 v[140:143], v140 offset:3072
	s_add_u32 s36, s74, 0x40000
	s_addc_u32 s37, s75, 0
	s_mov_b32 m0, s85
	v_lshl_add_u64 v[220:221], s[36:37], 0, v[148:149]
	ds_read_b128 v[156:159], v217 offset:32768
	ds_read_b128 v[160:163], v217 offset:33792
	ds_read_b128 v[164:167], v217 offset:34816
	ds_read_b128 v[188:191], v217 offset:35840
	ds_read_b128 v[192:195], v217 offset:36864
	ds_read_b128 v[196:199], v217 offset:37888
	ds_read_b128 v[200:203], v217 offset:38912
	ds_read_b128 v[204:207], v217 offset:39936
	global_load_lds_dwordx4 v[220:221], off
	v_lshl_add_u64 v[220:221], s[36:37], 0, v[146:147]
	s_mov_b32 m0, s86
	s_nop 0
	global_load_lds_dwordx4 v[220:221], off
	s_waitcnt lgkmcnt(8)
	s_barrier
	s_waitcnt lgkmcnt(0)
	s_setprio 1
	s_waitcnt lgkmcnt(0)
	v_mfma_f32_16x16x32_bf16 v[124:127], v[128:131], v[156:159], v[124:127]
	v_mfma_f32_16x16x32_bf16 v[120:123], v[136:139], v[156:159], v[120:123]
	v_mfma_f32_16x16x32_bf16 v[108:111], v[128:131], v[164:167], v[108:111]
	v_mfma_f32_16x16x32_bf16 v[104:107], v[136:139], v[164:167], v[104:107]
	v_mfma_f32_16x16x32_bf16 v[92:95], v[128:131], v[192:195], v[92:95]
	v_mfma_f32_16x16x32_bf16 v[88:91], v[136:139], v[192:195], v[88:91]
	v_mfma_f32_16x16x32_bf16 v[76:79], v[128:131], v[200:203], v[76:79]
	v_mfma_f32_16x16x32_bf16 v[72:75], v[136:139], v[200:203], v[72:75]
	v_mfma_f32_16x16x32_bf16 v[124:127], v[132:135], v[160:163], v[124:127]
	v_mfma_f32_16x16x32_bf16 v[120:123], v[140:143], v[160:163], v[120:123]
	v_mfma_f32_16x16x32_bf16 v[108:111], v[132:135], v[188:191], v[108:111]
	v_mfma_f32_16x16x32_bf16 v[104:107], v[140:143], v[188:191], v[104:107]
	v_mfma_f32_16x16x32_bf16 v[92:95], v[132:135], v[196:199], v[92:95]
	v_mfma_f32_16x16x32_bf16 v[88:91], v[140:143], v[196:199], v[88:91]
	v_mfma_f32_16x16x32_bf16 v[76:79], v[132:135], v[204:207], v[76:79]
	v_mfma_f32_16x16x32_bf16 v[72:75], v[140:143], v[204:207], v[72:75]
	s_setprio 0
	s_barrier
	s_add_i32 s35, 0, 0x1c000
	s_add_i32 s27, s27, s81
	v_add_u32_e32 v144, s35, v216
	v_lshl_add_u64 v[168:169], v[168:169], 0, s[18:19]
	s_mov_b32 m0, s27
	ds_read_b128 v[220:223], v144
	ds_read_b128 v[228:231], v144 offset:1024
	ds_read_b128 v[232:235], v144 offset:2048
	ds_read_b128 v[236:239], v144 offset:3072
	global_load_lds_dwordx4 v[168:169], off
	v_lshl_add_u64 v[168:169], v[176:177], 0, s[18:19]
	s_add_i32 m0, s27, 0x2000
	s_nop 0
	global_load_lds_dwordx4 v[168:169], off
	s_barrier
	s_waitcnt lgkmcnt(0)
	s_setprio 1
	s_waitcnt lgkmcnt(0)
	v_mfma_f32_16x16x32_bf16 v[116:119], v[220:223], v[156:159], v[116:119]
	v_mfma_f32_16x16x32_bf16 v[112:115], v[232:235], v[156:159], v[112:115]
	v_mfma_f32_16x16x32_bf16 v[100:103], v[220:223], v[164:167], v[100:103]
	v_mfma_f32_16x16x32_bf16 v[96:99], v[232:235], v[164:167], v[96:99]
	v_mfma_f32_16x16x32_bf16 v[84:87], v[220:223], v[192:195], v[84:87]
	v_mfma_f32_16x16x32_bf16 v[80:83], v[232:235], v[192:195], v[80:83]
	v_mfma_f32_16x16x32_bf16 v[68:71], v[220:223], v[200:203], v[68:71]
	v_mfma_f32_16x16x32_bf16 v[64:67], v[232:235], v[200:203], v[64:67]
	v_mfma_f32_16x16x32_bf16 v[116:119], v[228:231], v[160:163], v[116:119]
	v_mfma_f32_16x16x32_bf16 v[112:115], v[236:239], v[160:163], v[112:115]
	v_mfma_f32_16x16x32_bf16 v[100:103], v[228:231], v[188:191], v[100:103]
	v_mfma_f32_16x16x32_bf16 v[96:99], v[236:239], v[188:191], v[96:99]
	v_mfma_f32_16x16x32_bf16 v[84:87], v[228:231], v[196:199], v[84:87]
	v_mfma_f32_16x16x32_bf16 v[80:83], v[236:239], v[196:199], v[80:83]
	v_mfma_f32_16x16x32_bf16 v[68:71], v[228:231], v[204:207], v[68:71]
	v_mfma_f32_16x16x32_bf16 v[64:67], v[236:239], v[204:207], v[64:67]
	s_setprio 0
	s_mov_b32 m0, s87
	v_lshl_add_u64 v[168:169], v[224:225], 0, s[18:19]
	s_barrier
	ds_read_b128 v[156:159], v217 offset:49152
	ds_read_b128 v[160:163], v217 offset:50176
	ds_read_b128 v[164:167], v217 offset:51200
	ds_read_b128 v[188:191], v217 offset:52224
	ds_read_b128 v[192:195], v217 offset:53248
	ds_read_b128 v[196:199], v217 offset:54272
	ds_read_b128 v[200:203], v217 offset:55296
	ds_read_b128 v[204:207], v217 offset:56320
	global_load_lds_dwordx4 v[168:169], off
	v_lshl_add_u64 v[168:169], v[240:241], 0, s[18:19]
	s_mov_b32 m0, s79
	s_nop 0
	global_load_lds_dwordx4 v[168:169], off
	s_barrier
	s_waitcnt lgkmcnt(0)
	s_setprio 1
	s_waitcnt lgkmcnt(0)
	v_mfma_f32_16x16x32_bf16 v[60:63], v[128:131], v[156:159], v[60:63]
	v_mfma_f32_16x16x32_bf16 v[56:59], v[136:139], v[156:159], v[56:59]
	v_mfma_f32_16x16x32_bf16 v[44:47], v[128:131], v[164:167], v[44:47]
	v_mfma_f32_16x16x32_bf16 v[40:43], v[136:139], v[164:167], v[40:43]
	v_mfma_f32_16x16x32_bf16 v[28:31], v[128:131], v[192:195], v[28:31]
	v_mfma_f32_16x16x32_bf16 v[24:27], v[136:139], v[192:195], v[24:27]
	v_mfma_f32_16x16x32_bf16 v[12:15], v[128:131], v[200:203], v[12:15]
	v_mfma_f32_16x16x32_bf16 v[8:11], v[136:139], v[200:203], v[8:11]
	v_mfma_f32_16x16x32_bf16 v[60:63], v[132:135], v[160:163], v[60:63]
	v_mfma_f32_16x16x32_bf16 v[56:59], v[140:143], v[160:163], v[56:59]
	v_mfma_f32_16x16x32_bf16 v[44:47], v[132:135], v[188:191], v[44:47]
	v_mfma_f32_16x16x32_bf16 v[40:43], v[140:143], v[188:191], v[40:43]
	v_mfma_f32_16x16x32_bf16 v[28:31], v[132:135], v[196:199], v[28:31]
	v_mfma_f32_16x16x32_bf16 v[24:27], v[140:143], v[196:199], v[24:27]
	v_mfma_f32_16x16x32_bf16 v[12:15], v[132:135], v[204:207], v[12:15]
	v_mfma_f32_16x16x32_bf16 v[8:11], v[140:143], v[204:207], v[8:11]
	s_setprio 0
	s_barrier
	s_add_u32 s36, s72, 0x40080
	s_addc_u32 s37, s73, 0
	s_add_i32 s27, s35, s81
	v_lshl_add_u64 v[128:129], s[36:37], 0, v[148:149]
	s_mov_b32 m0, s27
	s_nop 0
	global_load_lds_dwordx4 v[128:129], off
	v_lshl_add_u64 v[128:129], s[36:37], 0, v[146:147]
	s_add_i32 m0, s27, 0x2000
	s_nop 0
	global_load_lds_dwordx4 v[128:129], off
	s_waitcnt vmcnt(6)
	s_barrier
	s_setprio 1
	v_mfma_f32_16x16x32_bf16 v[52:55], v[220:223], v[156:159], v[52:55]
	v_mfma_f32_16x16x32_bf16 v[48:51], v[232:235], v[156:159], v[48:51]
	v_mfma_f32_16x16x32_bf16 v[36:39], v[220:223], v[164:167], v[36:39]
	v_mfma_f32_16x16x32_bf16 v[32:35], v[232:235], v[164:167], v[32:35]
	v_mfma_f32_16x16x32_bf16 v[20:23], v[220:223], v[192:195], v[20:23]
	v_mfma_f32_16x16x32_bf16 v[16:19], v[232:235], v[192:195], v[16:19]
	v_mfma_f32_16x16x32_bf16 v[4:7], v[220:223], v[200:203], v[4:7]
	v_mfma_f32_16x16x32_bf16 v[0:3], v[232:235], v[200:203], v[0:3]
	v_mfma_f32_16x16x32_bf16 v[52:55], v[228:231], v[160:163], v[52:55]
	v_mfma_f32_16x16x32_bf16 v[48:51], v[236:239], v[160:163], v[48:51]
	v_mfma_f32_16x16x32_bf16 v[36:39], v[228:231], v[188:191], v[36:39]
	v_mfma_f32_16x16x32_bf16 v[32:35], v[236:239], v[188:191], v[32:35]
	v_mfma_f32_16x16x32_bf16 v[20:23], v[228:231], v[196:199], v[20:23]
	v_mfma_f32_16x16x32_bf16 v[16:19], v[236:239], v[196:199], v[16:19]
	v_mfma_f32_16x16x32_bf16 v[4:7], v[228:231], v[204:207], v[4:7]
	v_mfma_f32_16x16x32_bf16 v[0:3], v[236:239], v[204:207], v[0:3]
	s_setprio 0
	s_add_i32 s34, s34, 2
	s_add_u32 s52, s52, 0x100
	s_addc_u32 s53, s53, 0
	s_add_u32 s31, s31, 0x100
	s_addc_u32 s33, s33, 0
	s_cmp_gt_u32 s34, 13
	s_barrier

.LBB0_350:
	s_lshl_b32 s25, s84, 1
	s_add_i32 s25, s85, s25
	s_and_b32 s85, s25, 3
	s_lshl_b32 s25, s85, 19
	s_add_u32 s92, s74, s25
	v_cmp_lt_i64_e32 vcc, s[52:53], v[180:181]
	s_addc_u32 s93, s75, 0
	s_and_b64 s[30:31], vcc, exec
	s_cselect_b32 s25, s93, s1
	s_cselect_b32 s30, s92, s0
	s_ashr_i32 s47, s46, 31
	s_lshl_b64 s[34:35], s[46:47], 19
	s_add_u32 s94, s54, s34
	s_addc_u32 s95, s55, s35
	s_and_b64 s[34:35], vcc, exec
	s_cselect_b32 s31, s95, s51
	s_cselect_b32 s33, s94, s50
	s_add_u32 s0, s0, 0x40080
	s_addc_u32 s1, s1, 0
	s_add_u32 s34, s50, 0x100
	s_addc_u32 s35, s51, 0
	s_mov_b32 s36, -2
	s_add_u32 s27, s0, 0xfffc0080
	s_addc_u32 s37, s1, -1
	s_add_i32 s47, 0, 0x10000
	v_add_u32_e32 v140, s47, v192
	ds_read_b128 v[128:131], v140
	ds_read_b128 v[132:135], v140 offset:1024
	ds_read_b128 v[136:139], v140 offset:2048
	ds_read_b128 v[140:143], v140 offset:3072
	s_cmp_eq_u32 s36, 12
	s_cselect_b32 s53, s25, s37
	s_cselect_b32 s52, s30, s27
	s_cselect_b32 s51, s31, s35
	s_cselect_b32 s50, s33, s34
	v_lshl_add_u64 v[176:177], s[0:1], 0, v[156:157]
	s_add_i32 m0, s77, 0xc000
	ds_read_b128 v[162:165], v194
	ds_read_b128 v[166:169], v194 offset:1024
	ds_read_b128 v[196:199], v194 offset:2048
	ds_read_b128 v[200:203], v194 offset:3072
	ds_read_b128 v[204:207], v194 offset:4096
	ds_read_b128 v[216:219], v194 offset:5120
	ds_read_b128 v[220:223], v194 offset:6144
	ds_read_b128 v[228:231], v194 offset:7168
	global_load_lds_dwordx4 v[176:177], off
	v_lshl_add_u64 v[176:177], s[0:1], 0, v[158:159]
	s_add_i32 m0, s77, 0xe000
	s_nop 0
	global_load_lds_dwordx4 v[176:177], off
	s_waitcnt lgkmcnt(8)
	s_barrier
	s_waitcnt lgkmcnt(0)
	s_setprio 1
	s_waitcnt lgkmcnt(0)
	v_mfma_f32_16x16x32_bf16 v[124:127], v[128:131], v[162:165], 0
	v_mfma_f32_16x16x32_bf16 v[120:123], v[136:139], v[162:165], 0
	v_mfma_f32_16x16x32_bf16 v[116:119], v[128:131], v[196:199], 0
	v_mfma_f32_16x16x32_bf16 v[112:115], v[136:139], v[196:199], 0
	v_mfma_f32_16x16x32_bf16 v[108:111], v[128:131], v[204:207], 0
	v_mfma_f32_16x16x32_bf16 v[104:107], v[136:139], v[204:207], 0
	v_mfma_f32_16x16x32_bf16 v[100:103], v[128:131], v[220:223], 0
	v_mfma_f32_16x16x32_bf16 v[96:99], v[136:139], v[220:223], 0
	v_mfma_f32_16x16x32_bf16 v[124:127], v[132:135], v[166:169], v[124:127]
	v_mfma_f32_16x16x32_bf16 v[120:123], v[140:143], v[166:169], v[120:123]
	v_mfma_f32_16x16x32_bf16 v[116:119], v[132:135], v[200:203], v[116:119]
	v_mfma_f32_16x16x32_bf16 v[112:115], v[140:143], v[200:203], v[112:115]
	v_mfma_f32_16x16x32_bf16 v[108:111], v[132:135], v[216:219], v[108:111]
	v_mfma_f32_16x16x32_bf16 v[104:107], v[140:143], v[216:219], v[104:107]
	v_mfma_f32_16x16x32_bf16 v[100:103], v[132:135], v[228:231], v[100:103]
	v_mfma_f32_16x16x32_bf16 v[96:99], v[140:143], v[228:231], v[96:99]
	s_setprio 0
	s_barrier
	s_add_i32 s27, 0, 0x14000
	s_add_i32 s37, s47, s76
	v_add_u32_e32 v161, s27, v192
	v_lshl_add_u64 v[176:177], s[50:51], 0, v[148:149]
	s_mov_b32 m0, s37
	ds_read_b128 v[232:235], v161
	ds_read_b128 v[236:239], v161 offset:1024
	ds_read_b128 v[240:243], v161 offset:2048
	ds_read_b128 v[244:247], v161 offset:3072
	global_load_lds_dwordx4 v[176:177], off
	v_lshl_add_u64 v[188:189], s[50:51], 0, v[152:153]
	s_add_i32 m0, s37, 0x2000
	s_nop 0
	global_load_lds_dwordx4 v[188:189], off
	s_barrier
	s_waitcnt lgkmcnt(0)
	s_setprio 1
	s_waitcnt lgkmcnt(0)
	v_mfma_f32_16x16x32_bf16 v[92:95], v[232:235], v[162:165], 0
	v_mfma_f32_16x16x32_bf16 v[88:91], v[240:243], v[162:165], 0
	v_mfma_f32_16x16x32_bf16 v[84:87], v[232:235], v[196:199], 0
	v_mfma_f32_16x16x32_bf16 v[80:83], v[240:243], v[196:199], 0
	v_mfma_f32_16x16x32_bf16 v[76:79], v[232:235], v[204:207], 0
	v_mfma_f32_16x16x32_bf16 v[72:75], v[240:243], v[204:207], 0
	v_mfma_f32_16x16x32_bf16 v[68:71], v[232:235], v[220:223], 0
	v_mfma_f32_16x16x32_bf16 v[64:67], v[240:243], v[220:223], 0
	v_mfma_f32_16x16x32_bf16 v[92:95], v[236:239], v[166:169], v[92:95]
	v_mfma_f32_16x16x32_bf16 v[88:91], v[244:247], v[166:169], v[88:91]
	v_mfma_f32_16x16x32_bf16 v[84:87], v[236:239], v[200:203], v[84:87]
	v_mfma_f32_16x16x32_bf16 v[80:83], v[244:247], v[200:203], v[80:83]
	v_mfma_f32_16x16x32_bf16 v[76:79], v[236:239], v[216:219], v[76:79]
	v_mfma_f32_16x16x32_bf16 v[72:75], v[244:247], v[216:219], v[72:75]
	v_mfma_f32_16x16x32_bf16 v[68:71], v[236:239], v[228:231], v[68:71]
	v_mfma_f32_16x16x32_bf16 v[64:67], v[244:247], v[228:231], v[64:67]
	s_setprio 0
	s_mov_b32 m0, s77
	v_lshl_add_u64 v[224:225], s[52:53], 0, v[146:147]
	s_barrier
	ds_read_b128 v[162:165], v194 offset:16384
	ds_read_b128 v[166:169], v194 offset:17408
	ds_read_b128 v[196:199], v194 offset:18432
	ds_read_b128 v[200:203], v194 offset:19456
	ds_read_b128 v[204:207], v194 offset:20480
	ds_read_b128 v[216:219], v194 offset:21504
	ds_read_b128 v[220:223], v194 offset:22528
	ds_read_b128 v[228:231], v194 offset:23552
	global_load_lds_dwordx4 v[224:225], off
	v_lshl_add_u64 v[248:249], s[52:53], 0, v[150:151]
	s_mov_b32 m0, s78
	s_nop 0
	global_load_lds_dwordx4 v[248:249], off
	s_barrier
	s_waitcnt lgkmcnt(0)
	s_setprio 1
	s_waitcnt lgkmcnt(0)
	v_mfma_f32_16x16x32_bf16 v[60:63], v[128:131], v[162:165], 0
	v_mfma_f32_16x16x32_bf16 v[56:59], v[136:139], v[162:165], 0
	v_mfma_f32_16x16x32_bf16 v[52:55], v[128:131], v[196:199], 0
	v_mfma_f32_16x16x32_bf16 v[48:51], v[136:139], v[196:199], 0
	v_mfma_f32_16x16x32_bf16 v[44:47], v[128:131], v[204:207], 0
	v_mfma_f32_16x16x32_bf16 v[40:43], v[136:139], v[204:207], 0
	v_mfma_f32_16x16x32_bf16 v[36:39], v[128:131], v[220:223], 0
	v_mfma_f32_16x16x32_bf16 v[32:35], v[136:139], v[220:223], 0
	v_mfma_f32_16x16x32_bf16 v[60:63], v[132:135], v[166:169], v[60:63]
	v_mfma_f32_16x16x32_bf16 v[56:59], v[140:143], v[166:169], v[56:59]
	v_mfma_f32_16x16x32_bf16 v[52:55], v[132:135], v[200:203], v[52:55]
	v_mfma_f32_16x16x32_bf16 v[48:51], v[140:143], v[200:203], v[48:51]
	v_mfma_f32_16x16x32_bf16 v[44:47], v[132:135], v[216:219], v[44:47]
	v_mfma_f32_16x16x32_bf16 v[40:43], v[140:143], v[216:219], v[40:43]
	v_mfma_f32_16x16x32_bf16 v[36:39], v[132:135], v[228:231], v[36:39]
	v_mfma_f32_16x16x32_bf16 v[32:35], v[140:143], v[228:231], v[32:35]
	s_setprio 0
	s_barrier
	s_add_u32 s56, s50, 0x40000
	s_addc_u32 s57, s51, 0
	s_add_i32 s27, s27, s76
	v_lshl_add_u64 v[128:129], s[56:57], 0, v[148:149]
	s_mov_b32 m0, s27
	s_nop 0
	global_load_lds_dwordx4 v[128:129], off
	v_lshl_add_u64 v[128:129], s[56:57], 0, v[152:153]
	s_add_i32 m0, s27, 0x2000
	s_nop 0
	global_load_lds_dwordx4 v[128:129], off
	s_waitcnt vmcnt(6)
	s_barrier
	s_setprio 1
	v_mfma_f32_16x16x32_bf16 v[28:31], v[232:235], v[162:165], 0
	v_mfma_f32_16x16x32_bf16 v[24:27], v[240:243], v[162:165], 0
	v_mfma_f32_16x16x32_bf16 v[20:23], v[232:235], v[196:199], 0
	v_mfma_f32_16x16x32_bf16 v[16:19], v[240:243], v[196:199], 0
	v_mfma_f32_16x16x32_bf16 v[12:15], v[232:235], v[204:207], 0
	v_mfma_f32_16x16x32_bf16 v[8:11], v[240:243], v[204:207], 0
	v_mfma_f32_16x16x32_bf16 v[4:7], v[232:235], v[220:223], 0
	v_mfma_f32_16x16x32_bf16 v[0:3], v[240:243], v[220:223], 0
	v_mfma_f32_16x16x32_bf16 v[28:31], v[236:239], v[166:169], v[28:31]
	v_mfma_f32_16x16x32_bf16 v[24:27], v[244:247], v[166:169], v[24:27]
	v_mfma_f32_16x16x32_bf16 v[20:23], v[236:239], v[200:203], v[20:23]
	v_mfma_f32_16x16x32_bf16 v[16:19], v[244:247], v[200:203], v[16:19]
	v_mfma_f32_16x16x32_bf16 v[12:15], v[236:239], v[216:219], v[12:15]
	v_mfma_f32_16x16x32_bf16 v[8:11], v[244:247], v[216:219], v[8:11]
	v_mfma_f32_16x16x32_bf16 v[4:7], v[236:239], v[228:231], v[4:7]
	v_mfma_f32_16x16x32_bf16 v[0:3], v[244:247], v[228:231], v[0:3]
	s_setprio 0
	s_add_i32 s27, 0, 0x18000
	v_add_u32_e32 v140, s27, v192
	s_barrier
	ds_read_b128 v[128:131], v140
	ds_read_b128 v[132:135], v140 offset:1024
	ds_read_b128 v[136:139], v140 offset:2048
	ds_read_b128 v[140:143], v140 offset:3072
	s_add_u32 s52, s52, 0x40000
	s_addc_u32 s53, s53, 0
	s_mov_b32 m0, s81
	v_lshl_add_u64 v[232:233], s[52:53], 0, v[146:147]
	ds_read_b128 v[162:165], v194 offset:32768
	ds_read_b128 v[166:169], v194 offset:33792
	ds_read_b128 v[196:199], v194 offset:34816
	ds_read_b128 v[200:203], v194 offset:35840
	ds_read_b128 v[204:207], v194 offset:36864
	ds_read_b128 v[216:219], v194 offset:37888
	ds_read_b128 v[220:223], v194 offset:38912
	ds_read_b128 v[228:231], v194 offset:39936
	global_load_lds_dwordx4 v[232:233], off
	v_lshl_add_u64 v[232:233], s[52:53], 0, v[150:151]
	s_mov_b32 m0, s82
	s_nop 0
	global_load_lds_dwordx4 v[232:233], off
	s_waitcnt lgkmcnt(8)
	s_barrier
	s_waitcnt lgkmcnt(0)
	s_setprio 1
	s_waitcnt lgkmcnt(0)
	v_mfma_f32_16x16x32_bf16 v[124:127], v[128:131], v[162:165], v[124:127]
	v_mfma_f32_16x16x32_bf16 v[120:123], v[136:139], v[162:165], v[120:123]
	v_mfma_f32_16x16x32_bf16 v[116:119], v[128:131], v[196:199], v[116:119]
	v_mfma_f32_16x16x32_bf16 v[112:115], v[136:139], v[196:199], v[112:115]
	v_mfma_f32_16x16x32_bf16 v[108:111], v[128:131], v[204:207], v[108:111]
	v_mfma_f32_16x16x32_bf16 v[104:107], v[136:139], v[204:207], v[104:107]
	v_mfma_f32_16x16x32_bf16 v[100:103], v[128:131], v[220:223], v[100:103]
	v_mfma_f32_16x16x32_bf16 v[96:99], v[136:139], v[220:223], v[96:99]
	v_mfma_f32_16x16x32_bf16 v[124:127], v[132:135], v[166:169], v[124:127]
	v_mfma_f32_16x16x32_bf16 v[120:123], v[140:143], v[166:169], v[120:123]
	v_mfma_f32_16x16x32_bf16 v[116:119], v[132:135], v[200:203], v[116:119]
	v_mfma_f32_16x16x32_bf16 v[112:115], v[140:143], v[200:203], v[112:115]
	v_mfma_f32_16x16x32_bf16 v[108:111], v[132:135], v[216:219], v[108:111]
	v_mfma_f32_16x16x32_bf16 v[104:107], v[140:143], v[216:219], v[104:107]
	v_mfma_f32_16x16x32_bf16 v[100:103], v[132:135], v[228:231], v[100:103]
	v_mfma_f32_16x16x32_bf16 v[96:99], v[140:143], v[228:231], v[96:99]
	s_setprio 0
	s_barrier
	s_add_i32 s37, 0, 0x1c000
	s_add_i32 s27, s27, s76
	v_add_u32_e32 v161, s37, v192
	v_lshl_add_u64 v[176:177], v[176:177], 0, s[18:19]
	s_mov_b32 m0, s27
	ds_read_b128 v[232:235], v161
	ds_read_b128 v[236:239], v161 offset:1024
	ds_read_b128 v[240:243], v161 offset:2048
	ds_read_b128 v[244:247], v161 offset:3072
	global_load_lds_dwordx4 v[176:177], off
	v_lshl_add_u64 v[176:177], v[188:189], 0, s[18:19]
	s_add_i32 m0, s27, 0x2000
	s_nop 0
	global_load_lds_dwordx4 v[176:177], off
	s_barrier
	s_waitcnt lgkmcnt(0)
	s_setprio 1
	s_waitcnt lgkmcnt(0)
	v_mfma_f32_16x16x32_bf16 v[92:95], v[232:235], v[162:165], v[92:95]
	v_mfma_f32_16x16x32_bf16 v[88:91], v[240:243], v[162:165], v[88:91]
	v_mfma_f32_16x16x32_bf16 v[84:87], v[232:235], v[196:199], v[84:87]
	v_mfma_f32_16x16x32_bf16 v[80:83], v[240:243], v[196:199], v[80:83]
	v_mfma_f32_16x16x32_bf16 v[76:79], v[232:235], v[204:207], v[76:79]
	v_mfma_f32_16x16x32_bf16 v[72:75], v[240:243], v[204:207], v[72:75]
	v_mfma_f32_16x16x32_bf16 v[68:71], v[232:235], v[220:223], v[68:71]
	v_mfma_f32_16x16x32_bf16 v[64:67], v[240:243], v[220:223], v[64:67]
	v_mfma_f32_16x16x32_bf16 v[92:95], v[236:239], v[166:169], v[92:95]
	v_mfma_f32_16x16x32_bf16 v[88:91], v[244:247], v[166:169], v[88:91]
	v_mfma_f32_16x16x32_bf16 v[84:87], v[236:239], v[200:203], v[84:87]
	v_mfma_f32_16x16x32_bf16 v[80:83], v[244:247], v[200:203], v[80:83]
	v_mfma_f32_16x16x32_bf16 v[76:79], v[236:239], v[216:219], v[76:79]
	v_mfma_f32_16x16x32_bf16 v[72:75], v[244:247], v[216:219], v[72:75]
	v_mfma_f32_16x16x32_bf16 v[68:71], v[236:239], v[228:231], v[68:71]
	v_mfma_f32_16x16x32_bf16 v[64:67], v[244:247], v[228:231], v[64:67]
	s_setprio 0
	s_mov_b32 m0, s80
	v_lshl_add_u64 v[176:177], v[224:225], 0, s[18:19]
	s_barrier
	ds_read_b128 v[162:165], v194 offset:49152
	ds_read_b128 v[166:169], v194 offset:50176
	ds_read_b128 v[196:199], v194 offset:51200
	ds_read_b128 v[200:203], v194 offset:52224
	ds_read_b128 v[204:207], v194 offset:53248
	ds_read_b128 v[216:219], v194 offset:54272
	ds_read_b128 v[220:223], v194 offset:55296
	ds_read_b128 v[228:231], v194 offset:56320
	global_load_lds_dwordx4 v[176:177], off
	v_lshl_add_u64 v[176:177], v[248:249], 0, s[18:19]
	s_mov_b32 m0, s83
	s_nop 0
	global_load_lds_dwordx4 v[176:177], off
	s_barrier
	s_waitcnt lgkmcnt(0)
	s_setprio 1
	s_waitcnt lgkmcnt(0)
	v_mfma_f32_16x16x32_bf16 v[60:63], v[128:131], v[162:165], v[60:63]
	v_mfma_f32_16x16x32_bf16 v[56:59], v[136:139], v[162:165], v[56:59]
	v_mfma_f32_16x16x32_bf16 v[52:55], v[128:131], v[196:199], v[52:55]
	v_mfma_f32_16x16x32_bf16 v[48:51], v[136:139], v[196:199], v[48:51]
	v_mfma_f32_16x16x32_bf16 v[44:47], v[128:131], v[204:207], v[44:47]
	v_mfma_f32_16x16x32_bf16 v[40:43], v[136:139], v[204:207], v[40:43]
	v_mfma_f32_16x16x32_bf16 v[36:39], v[128:131], v[220:223], v[36:39]
	v_mfma_f32_16x16x32_bf16 v[32:35], v[136:139], v[220:223], v[32:35]
	v_mfma_f32_16x16x32_bf16 v[60:63], v[132:135], v[166:169], v[60:63]
	v_mfma_f32_16x16x32_bf16 v[56:59], v[140:143], v[166:169], v[56:59]
	v_mfma_f32_16x16x32_bf16 v[52:55], v[132:135], v[200:203], v[52:55]
	v_mfma_f32_16x16x32_bf16 v[48:51], v[140:143], v[200:203], v[48:51]
	v_mfma_f32_16x16x32_bf16 v[44:47], v[132:135], v[216:219], v[44:47]
	v_mfma_f32_16x16x32_bf16 v[40:43], v[140:143], v[216:219], v[40:43]
	v_mfma_f32_16x16x32_bf16 v[36:39], v[132:135], v[228:231], v[36:39]
	v_mfma_f32_16x16x32_bf16 v[32:35], v[140:143], v[228:231], v[32:35]
	s_setprio 0
	s_barrier
	s_add_u32 s50, s50, 0x40080
	s_addc_u32 s51, s51, 0
	s_add_i32 s27, s37, s76
	v_lshl_add_u64 v[128:129], s[50:51], 0, v[148:149]
	s_mov_b32 m0, s27
	s_nop 0
	global_load_lds_dwordx4 v[128:129], off
	v_lshl_add_u64 v[128:129], s[50:51], 0, v[152:153]
	s_add_i32 m0, s27, 0x2000
	s_nop 0
	global_load_lds_dwordx4 v[128:129], off
	s_waitcnt vmcnt(6)
	s_barrier
	s_setprio 1
	v_mfma_f32_16x16x32_bf16 v[28:31], v[232:235], v[162:165], v[28:31]
	v_mfma_f32_16x16x32_bf16 v[24:27], v[240:243], v[162:165], v[24:27]
	v_mfma_f32_16x16x32_bf16 v[20:23], v[232:235], v[196:199], v[20:23]
	v_mfma_f32_16x16x32_bf16 v[16:19], v[240:243], v[196:199], v[16:19]
	v_mfma_f32_16x16x32_bf16 v[12:15], v[232:235], v[204:207], v[12:15]
	v_mfma_f32_16x16x32_bf16 v[8:11], v[240:243], v[204:207], v[8:11]
	v_mfma_f32_16x16x32_bf16 v[4:7], v[232:235], v[220:223], v[4:7]
	v_mfma_f32_16x16x32_bf16 v[0:3], v[240:243], v[220:223], v[0:3]
	v_mfma_f32_16x16x32_bf16 v[28:31], v[236:239], v[166:169], v[28:31]
	v_mfma_f32_16x16x32_bf16 v[24:27], v[244:247], v[166:169], v[24:27]
	v_mfma_f32_16x16x32_bf16 v[20:23], v[236:239], v[200:203], v[20:23]
	v_mfma_f32_16x16x32_bf16 v[16:19], v[244:247], v[200:203], v[16:19]
	v_mfma_f32_16x16x32_bf16 v[12:15], v[236:239], v[216:219], v[12:15]
	v_mfma_f32_16x16x32_bf16 v[8:11], v[244:247], v[216:219], v[8:11]
	v_mfma_f32_16x16x32_bf16 v[4:7], v[236:239], v[228:231], v[4:7]
	v_mfma_f32_16x16x32_bf16 v[0:3], v[244:247], v[228:231], v[0:3]
	s_setprio 0
	s_add_i32 s36, s36, 2
	s_add_u32 s0, s0, 0x100
	s_addc_u32 s1, s1, 0
	s_add_u32 s34, s34, 0x100
	s_addc_u32 s35, s35, 0
	s_cmp_gt_u32 s36, 13
	s_barrier
